# QKV epilogue: gains via LDS slot, cos-sin prefetch one row ahead
# speedup vs baseline: 1.0228x; 1.0228x over previous
.LBB0_800:
	s_lshl_b32 s13, s20, 8
	s_add_i32 s13, s13, s46
	s_cmp_lt_u32 s38, 4
	v_mov_b32_e32 v22, v171
	v_mov_b32_e32 v23, v1
	s_waitcnt lgkmcnt(0)
	s_cselect_b32 s15, s0, s2
	s_nop 0
	v_add_u32_e32 v186, s13, v22
	s_cselect_b32 s13, s1, s3
	s_add_u32 s26, s15, s10
	s_addc_u32 s27, s13, s11
	s_ashr_i32 s13, s20, 5
	s_mul_hi_i32 s15, s13, 0x9000
	s_mul_i32 s13, s13, 0x9000
	s_add_u32 s13, s52, s13
	s_addc_u32 s15, s53, s15
	s_lshl_b32 s20, s38, 8
	s_or_b32 s20, s20, s50
	s_ashr_i32 s21, s20, 31
	s_lshl_b64 s[24:25], s[20:21], 2
	v_lshlrev_b32_e32 v180, 3, v23
	s_add_u32 s24, s13, s24
	v_ashrrev_i32_e32 v181, 31, v180
	s_addc_u32 s25, s15, s25
	v_lshlrev_b64 v[182:183], 2, v[180:181]
	v_ashrrev_i32_e32 v187, 31, v186
	v_lshl_add_u64 v[34:35], v[186:187], 2, s[6:7]
	v_lshl_add_u64 v[46:47], s[24:25], 0, v[182:183]
	global_load_dword v146, v[34:35], off
	global_load_dwordx4 v[22:25], v[46:47], off offset:16
	global_load_dwordx4 v[42:45], v[46:47], off
	global_load_dword v214, v[34:35], off offset:64
	global_load_dword v213, v[34:35], off offset:128
	global_load_dword v212, v[34:35], off offset:192
	global_load_dword v211, v[34:35], off offset:512
	global_load_dword v210, v[34:35], off offset:576
	global_load_dword v209, v[34:35], off offset:640
	global_load_dword v187, v[34:35], off offset:704
	s_nop 0
	global_load_dwordx4 v[34:37], v[46:47], off offset:144
	s_nop 0
	global_load_dwordx4 v[46:49], v[46:47], off offset:128
	s_cmp_lt_i32 s38, 8
	s_cselect_b64 s[24:25], -1, 0
	v_and_b32_e32 v222, 15, v224
	v_lshlrev_b32_e32 v220, 4, v222
	v_mov_b32_e32 v221, 0
	v_lshl_add_u64 v[220:221], s[26:27], 0, v[220:221]
	global_load_dwordx4 v[192:195], v[220:221], off
	v_lshrrev_b32_e64 v215, 2, s41
	v_lshl_add_u32 v235, v222, 4, v215
	v_add_u32_e32 v235, 0x20000, v235
	v_lshrrev_b32_e32 v222, 4, v224
	v_lshl_add_u32 v215, v222, 5, v215
	v_add_u32_e32 v215, 0x20000, v215
	v_readlane_b32 s26, v254, 23
	v_readlane_b32 s27, v254, 24
	s_nop 1
	v_lshl_add_u64 v[168:169], s[26:27], 0, v[182:183]
	v_lshlrev_b32_e32 v222, 7, v186
	v_and_b32_e32 v222, 0xfff80, v222
	v_mad_u64_u32 v[220:221], vcc, v222, 1, v[168:169]
	global_load_dwordx4 v[240:243], v[220:221], off offset:16
	global_load_dwordx4 v[236:239], v[220:221], off
	v_add_co_u32_e32 v220, vcc, 0x100000, v220
	s_nop 1
	v_addc_co_u32_e32 v221, vcc, 0, v221, vcc
	global_load_dwordx4 v[248:251], v[220:221], off offset:16
	global_load_dwordx4 v[244:247], v[220:221], off
	s_cmp_gt_i32 s38, 7
	s_waitcnt vmcnt(0)
	ds_write_b128 v235, v[192:195]
	v_fmamk_f32 v146, v146, 0x3a800000, v223
	v_mul_f32_e32 v147, 0x4b800000, v146
	v_cmp_gt_f32_e32 vcc, s95, v146
	s_nop 1
	v_cndmask_b32_e32 v146, v146, v147, vcc
	v_rsq_f32_e32 v146, v146
	s_nop 0
	v_mul_f32_e32 v147, 0x45800000, v146
	v_cndmask_b32_e32 v146, v146, v147, vcc
	v_pk_fma_f32 v[190:191], v[138:139], v[146:147], v[46:47] op_sel_hi:[1,0,1]
	v_fma_f32 v139, v132, v146, v36
	v_mov_b32_e32 v132, v137
	v_mov_b32_e32 v188, v25
	v_mov_b32_e32 v189, v37
	v_pk_fma_f32 v[192:193], v[142:143], v[146:147], v[42:43] op_sel_hi:[1,0,1]
	v_pk_fma_f32 v[198:199], v[134:135], v[146:147], v[22:23] op_sel_hi:[1,0,1]
	v_pk_fma_f32 v[202:203], v[130:131], v[146:147], v[34:35] op_sel_hi:[1,0,1]
	v_fma_f32 v134, v136, v146, v24
	v_pk_fma_f32 v[196:197], v[144:145], v[146:147], v[44:45] op_sel_hi:[1,0,1]
	v_pk_fma_f32 v[194:195], v[140:141], v[146:147], v[48:49] op_sel_hi:[1,0,1]
	v_pk_fma_f32 v[200:201], v[132:133], v[146:147], v[188:189] op_sel_hi:[1,0,1]
	s_cbranch_scc1 .LBB0_802
	v_pk_mul_f32 v[130:131], v[192:193], v[192:193]
	v_pk_mul_f32 v[132:133], v[196:197], v[196:197]
	v_add_f32_e32 v25, v130, v131
	v_add_f32_e32 v25, v132, v25
	v_pk_mul_f32 v[136:137], v[198:199], v[198:199]
	v_add_f32_e32 v25, v133, v25
	v_add_f32_e32 v25, v136, v25
	v_add_f32_e32 v25, v137, v25
	v_fmac_f32_e32 v25, v134, v134
	v_fmac_f32_e32 v25, v200, v200
	v_pk_mul_f32 v[130:131], v[190:191], v[190:191]
	v_mov_b32_e32 v138, v201
	v_add_f32_e32 v25, v130, v25
	v_add_f32_e32 v25, v131, v25
	v_pk_mul_f32 v[130:131], v[194:195], v[194:195]
	v_xor_b32_e32 v37, 16, v224
	v_add_f32_e32 v25, v130, v25
	v_add_f32_e32 v25, v131, v25
	v_pk_mul_f32 v[130:131], v[202:203], v[202:203]
	v_readlane_b32 s26, v254, 23
	v_add_f32_e32 v25, v130, v25
	v_add_f32_e32 v25, v131, v25
	v_pk_mul_f32 v[130:131], v[138:139], v[138:139]
	v_mov_b32_e32 v143, v0
	v_add_f32_e32 v25, v131, v25
	v_add_f32_e32 v25, v130, v25
	v_and_b32_e32 v130, 64, v224
	v_add_u32_e32 v130, 64, v130
	v_cmp_lt_i32_e32 vcc, v37, v130
	v_readlane_b32 s27, v254, 24
	s_nop 0
	v_cndmask_b32_e32 v37, v224, v37, vcc
	v_lshlrev_b32_e32 v37, 2, v37
	ds_bpermute_b32 v37, v37, v25
	s_waitcnt lgkmcnt(0)
	v_add_f32_e32 v25, v25, v37
	v_xor_b32_e32 v37, 32, v224
	v_cmp_lt_i32_e32 vcc, v37, v130
	ds_read_b128 v[130:133], v215 offset:16
	ds_read_b128 v[146:149], v215
	v_cndmask_b32_e32 v37, v224, v37, vcc
	v_lshlrev_b32_e32 v37, 2, v37
	ds_bpermute_b32 v37, v37, v25
	s_waitcnt lgkmcnt(0)
	v_add_f32_e32 v25, v25, v37
	v_fmamk_f32 v25, v25, 0x3c800000, v223
	v_cmp_gt_f32_e32 vcc, s95, v25
	v_mul_f32_e32 v37, 0x4b800000, v25
	s_nop 0
	v_cndmask_b32_e32 v25, v25, v37, vcc
	v_rsq_f32_e32 v25, v25
	s_nop 0
	v_mul_f32_e32 v37, 0x45800000, v25
	v_cndmask_b32_e32 v204, v25, v37, vcc
	v_mul_f32_e32 v25, v134, v204
	ds_read_b128 v[134:137], v215 offset:144
	ds_read_b128 v[150:153], v215 offset:128
	v_pk_mul_f32 v[190:191], v[190:191], v[204:205] op_sel_hi:[1,0]
	v_pk_mul_f32 v[192:193], v[192:193], v[204:205] op_sel_hi:[1,0]
	s_waitcnt lgkmcnt(3)
	v_mul_f32_e32 v132, v132, v25
	v_mul_f32_e32 v25, v139, v204
	s_waitcnt lgkmcnt(2)
	v_pk_mul_f32 v[146:147], v[146:147], v[192:193]
	s_waitcnt lgkmcnt(1)
	v_mul_f32_e32 v206, v136, v25
	v_lshlrev_b32_e32 v25, 7, v186
	v_and_b32_e32 v142, 0xfff80, v25
	v_lshl_add_u64 v[138:139], s[26:27], 0, v[142:143]
	v_readlane_b32 s26, v254, 25
	v_readlane_b32 s27, v254, 26
	v_lshl_add_u64 v[144:145], v[138:139], 0, v[182:183]
	v_lshl_add_u64 v[142:143], s[26:27], 0, v[142:143]
	v_lshl_add_u64 v[216:217], v[142:143], 0, v[182:183]
	s_waitcnt lgkmcnt(0)
	v_pk_mul_f32 v[150:151], v[150:151], v[190:191]
	v_mov_b32_e32 v136, v133
	s_waitcnt vmcnt(2)
	v_mov_b64_e32 v[154:155], v[236:237]
	v_mov_b64_e32 v[156:157], v[238:239]
	v_mov_b64_e32 v[138:139], v[240:241]
	v_mov_b64_e32 v[140:141], v[242:243]
	v_mov_b64_e32 v[216:217], v[244:245]
	v_mov_b64_e32 v[218:219], v[246:247]
	v_mov_b64_e32 v[142:143], v[248:249]
	v_mov_b64_e32 v[144:145], v[250:251]
	v_pk_mul_f32 v[190:191], v[216:217], v[150:151]
	v_pk_mul_f32 v[150:151], v[154:155], v[150:151]
	v_pk_fma_f32 v[192:193], v[154:155], v[146:147], v[190:191] neg_lo:[0,0,1] neg_hi:[0,0,1]
	v_pk_fma_f32 v[190:191], v[216:217], v[146:147], v[150:151]
	v_pk_mul_f32 v[146:147], v[196:197], v[204:205] op_sel_hi:[1,0]
	s_nop 0
	v_pk_mul_f32 v[146:147], v[148:149], v[146:147]
	v_pk_mul_f32 v[148:149], v[194:195], v[204:205] op_sel_hi:[1,0]
	s_nop 0
	v_pk_mul_f32 v[148:149], v[152:153], v[148:149]
	s_nop 0
	v_pk_mul_f32 v[150:151], v[218:219], v[148:149]
	v_pk_mul_f32 v[148:149], v[156:157], v[148:149]
	v_pk_fma_f32 v[196:197], v[156:157], v[146:147], v[150:151] neg_lo:[0,0,1] neg_hi:[0,0,1]
	v_pk_fma_f32 v[194:195], v[218:219], v[146:147], v[148:149]
	v_pk_mul_f32 v[146:147], v[198:199], v[204:205] op_sel_hi:[1,0]
	s_nop 0
	v_pk_mul_f32 v[130:131], v[130:131], v[146:147]
	v_pk_mul_f32 v[146:147], v[202:203], v[204:205] op_sel_hi:[1,0]
	s_nop 0
	v_pk_mul_f32 v[134:135], v[134:135], v[146:147]
	s_nop 0
	v_pk_mul_f32 v[146:147], v[142:143], v[134:135]
	v_pk_mul_f32 v[134:135], v[138:139], v[134:135]
	v_pk_fma_f32 v[198:199], v[138:139], v[130:131], v[146:147] neg_lo:[0,0,1] neg_hi:[0,0,1]
	v_pk_fma_f32 v[202:203], v[142:143], v[130:131], v[134:135]
	v_pk_mul_f32 v[134:135], v[200:201], v[204:205] op_sel_hi:[1,0]
	v_mul_f32_e32 v138, v140, v206
	v_pk_mul_f32 v[136:137], v[136:137], v[134:135]
	v_mul_f32_e32 v130, v144, v132
	v_mov_b32_e32 v207, v137
	v_mov_b32_e32 v133, v136
	v_pk_mul_f32 v[134:135], v[144:145], v[206:207]
	s_nop 0
	v_pk_fma_f32 v[134:135], v[140:141], v[132:133], v[134:135] neg_lo:[0,0,1] neg_hi:[0,0,1]
	v_mov_b32_e32 v140, v145
	v_pk_mul_f32 v[132:133], v[140:141], v[136:137]
	v_mov_b32_e32 v200, v135
	v_mov_b32_e32 v131, v132
	v_mov_b32_e32 v139, v133
	v_pk_add_f32 v[130:131], v[130:131], v[138:139]
	s_nop 0
	v_mov_b32_e32 v139, v130
	v_mov_b32_e32 v201, v131
	v_add_u32_e32 v222, 0x10, v186
	v_lshlrev_b32_e32 v222, 7, v222
	v_and_b32_e32 v222, 0xfff80, v222
	v_mad_u64_u32 v[220:221], vcc, v222, 1, v[168:169]
	global_load_dwordx4 v[240:243], v[220:221], off offset:16
	global_load_dwordx4 v[236:239], v[220:221], off
	v_add_co_u32_e32 v220, vcc, 0x100000, v220
	s_nop 1
	v_addc_co_u32_e32 v221, vcc, 0, v221, vcc
	global_load_dwordx4 v[248:251], v[220:221], off offset:16
	global_load_dwordx4 v[244:247], v[220:221], off
.LBB0_802:
	v_fmamk_f32 v25, v214, 0x3a800000, v223
	v_mul_f32_e32 v37, 0x4b800000, v25
	v_cmp_gt_f32_e32 vcc, s95, v25
	v_readlane_b32 s26, v254, 27
	v_readlane_b32 s27, v254, 28
	v_cndmask_b32_e32 v25, v25, v37, vcc
	v_rsq_f32_e32 v37, v25
	v_mov_b64_e32 v[130:131], s[26:27]
	v_mad_i64_i32 v[130:131], s[26:27], v186, s82, v[130:131]
	v_mul_f32_e32 v132, 0x45800000, v37
	v_lshl_add_u64 v[130:131], s[20:21], 1, v[130:131]
	v_cndmask_b32_e32 v136, v37, v132, vcc
	v_lshl_add_u64 v[140:141], v[180:181], 1, v[130:131]
	v_cvt_pk_bf16_f32 v130, v192, v193
	v_cvt_pk_bf16_f32 v131, v196, v197
	v_cvt_pk_bf16_f32 v132, v198, v199
	v_cvt_pk_bf16_f32 v133, v134, v200
	v_add_u32_e32 v25, 16, v186
	global_store_dwordx4 v[140:141], v[130:133], off
	s_nop 1
	v_cvt_pk_bf16_f32 v130, v190, v191
	v_cvt_pk_bf16_f32 v131, v194, v195
	v_cvt_pk_bf16_f32 v132, v202, v203
	v_cvt_pk_bf16_f32 v133, v139, v201
	global_store_dwordx4 v[140:141], v[130:133], off offset:64
	v_pk_fma_f32 v[142:143], v[122:123], v[136:137], v[46:47] op_sel_hi:[1,0,1]
	v_fma_f32 v123, v116, v136, v36
	v_mov_b32_e32 v116, v121
	v_cndmask_b32_e64 v37, 0, 1, s[24:25]
	v_pk_fma_f32 v[144:145], v[126:127], v[136:137], v[42:43] op_sel_hi:[1,0,1]
	v_pk_fma_f32 v[150:151], v[118:119], v[136:137], v[22:23] op_sel_hi:[1,0,1]
	v_pk_fma_f32 v[154:155], v[114:115], v[136:137], v[34:35] op_sel_hi:[1,0,1]
	v_fma_f32 v118, v120, v136, v24
	v_pk_fma_f32 v[148:149], v[128:129], v[136:137], v[44:45] op_sel_hi:[1,0,1]
	v_pk_fma_f32 v[146:147], v[124:125], v[136:137], v[48:49] op_sel_hi:[1,0,1]
	v_cmp_ne_u32_e64 s[38:39], 1, v37
	s_andn2_b64 vcc, exec, s[24:25]
	v_pk_fma_f32 v[152:153], v[116:117], v[136:137], v[188:189] op_sel_hi:[1,0,1]
	s_cbranch_vccnz .LBB0_804
	v_pk_mul_f32 v[114:115], v[144:145], v[144:145]
	v_pk_mul_f32 v[116:117], v[148:149], v[148:149]
	v_add_f32_e32 v37, v114, v115
	v_add_f32_e32 v37, v116, v37
	v_pk_mul_f32 v[120:121], v[150:151], v[150:151]
	v_add_f32_e32 v37, v117, v37
	v_add_f32_e32 v37, v120, v37
	v_add_f32_e32 v37, v121, v37
	v_fmac_f32_e32 v37, v118, v118
	v_fmac_f32_e32 v37, v152, v152
	v_pk_mul_f32 v[114:115], v[142:143], v[142:143]
	v_mov_b32_e32 v122, v153
	v_add_f32_e32 v37, v114, v37
	v_add_f32_e32 v37, v115, v37
	v_pk_mul_f32 v[114:115], v[146:147], v[146:147]
	v_readlane_b32 s24, v254, 23
	v_add_f32_e32 v37, v114, v37
	v_add_f32_e32 v37, v115, v37
	v_pk_mul_f32 v[114:115], v[154:155], v[154:155]
	v_mov_b32_e32 v127, v0
	v_add_f32_e32 v37, v114, v37
	v_add_f32_e32 v37, v115, v37
	v_pk_mul_f32 v[114:115], v[122:123], v[122:123]
	v_readlane_b32 s25, v254, 24
	v_add_f32_e32 v37, v115, v37
	v_and_b32_e32 v115, 64, v224
	v_add_f32_e32 v37, v114, v37
	v_xor_b32_e32 v114, 16, v224
	v_add_u32_e32 v115, 64, v115
	v_cmp_lt_i32_e32 vcc, v114, v115
	s_nop 1
	v_cndmask_b32_e32 v114, v224, v114, vcc
	v_lshlrev_b32_e32 v114, 2, v114
	ds_bpermute_b32 v114, v114, v37
	s_waitcnt lgkmcnt(0)
	v_add_f32_e32 v37, v37, v114
	v_xor_b32_e32 v114, 32, v224
	v_cmp_lt_i32_e32 vcc, v114, v115
	s_nop 1
	v_cndmask_b32_e32 v114, v224, v114, vcc
	v_lshlrev_b32_e32 v114, 2, v114
	ds_bpermute_b32 v114, v114, v37
	s_waitcnt lgkmcnt(0)
	v_add_f32_e32 v37, v37, v114
	v_fmamk_f32 v37, v37, 0x3c800000, v223
	v_cmp_gt_f32_e32 vcc, s95, v37
	v_mul_f32_e32 v114, 0x4b800000, v37
	s_nop 0
	v_cndmask_b32_e32 v37, v37, v114, vcc
	v_rsq_f32_e32 v37, v37
	s_nop 0
	v_mul_f32_e32 v114, 0x45800000, v37
	v_cndmask_b32_e32 v156, v37, v114, vcc
	ds_read_b128 v[114:117], v215 offset:16
	ds_read_b128 v[130:133], v215
	v_mul_f32_e32 v37, v118, v156
	ds_read_b128 v[118:121], v215 offset:144
	ds_read_b128 v[134:137], v215 offset:128
	v_pk_mul_f32 v[142:143], v[142:143], v[156:157] op_sel_hi:[1,0]
	v_pk_mul_f32 v[144:145], v[144:145], v[156:157] op_sel_hi:[1,0]
	s_waitcnt lgkmcnt(3)
	v_mul_f32_e32 v116, v116, v37
	v_mul_f32_e32 v37, v123, v156
	s_waitcnt lgkmcnt(1)
	v_mul_f32_e32 v190, v120, v37
	v_lshlrev_b32_e32 v37, 7, v25
	v_and_b32_e32 v126, 0xfff80, v37
	v_lshl_add_u64 v[122:123], s[24:25], 0, v[126:127]
	v_readlane_b32 s24, v254, 25
	v_readlane_b32 s25, v254, 26
	v_lshl_add_u64 v[128:129], v[122:123], 0, v[182:183]
	v_lshl_add_u64 v[126:127], s[24:25], 0, v[126:127]
	v_lshl_add_u64 v[192:193], v[126:127], 0, v[182:183]
	s_waitcnt lgkmcnt(0)
	v_pk_mul_f32 v[134:135], v[134:135], v[142:143]
	v_pk_mul_f32 v[130:131], v[130:131], v[144:145]
	v_mov_b32_e32 v120, v117
	s_waitcnt vmcnt(2)
	v_mov_b64_e32 v[138:139], v[236:237]
	v_mov_b64_e32 v[140:141], v[238:239]
	v_mov_b64_e32 v[122:123], v[240:241]
	v_mov_b64_e32 v[124:125], v[242:243]
	v_mov_b64_e32 v[192:193], v[244:245]
	v_mov_b64_e32 v[194:195], v[246:247]
	v_mov_b64_e32 v[126:127], v[248:249]
	v_mov_b64_e32 v[128:129], v[250:251]
	v_pk_mul_f32 v[142:143], v[192:193], v[134:135]
	v_pk_mul_f32 v[134:135], v[138:139], v[134:135]
	v_pk_fma_f32 v[144:145], v[138:139], v[130:131], v[142:143] neg_lo:[0,0,1] neg_hi:[0,0,1]
	v_pk_fma_f32 v[142:143], v[192:193], v[130:131], v[134:135]
	v_pk_mul_f32 v[130:131], v[148:149], v[156:157] op_sel_hi:[1,0]
	s_nop 0
	v_pk_mul_f32 v[130:131], v[132:133], v[130:131]
	v_pk_mul_f32 v[132:133], v[146:147], v[156:157] op_sel_hi:[1,0]
	s_nop 0
	v_pk_mul_f32 v[132:133], v[136:137], v[132:133]
	s_nop 0
	v_pk_mul_f32 v[134:135], v[194:195], v[132:133]
	v_pk_mul_f32 v[132:133], v[140:141], v[132:133]
	v_pk_fma_f32 v[148:149], v[140:141], v[130:131], v[134:135] neg_lo:[0,0,1] neg_hi:[0,0,1]
	v_pk_fma_f32 v[146:147], v[194:195], v[130:131], v[132:133]
	v_pk_mul_f32 v[130:131], v[150:151], v[156:157] op_sel_hi:[1,0]
	s_nop 0
	v_pk_mul_f32 v[114:115], v[114:115], v[130:131]
	v_pk_mul_f32 v[130:131], v[154:155], v[156:157] op_sel_hi:[1,0]
	s_nop 0
	v_pk_mul_f32 v[118:119], v[118:119], v[130:131]
	s_nop 0
	v_pk_mul_f32 v[130:131], v[126:127], v[118:119]
	v_pk_mul_f32 v[118:119], v[122:123], v[118:119]
	v_pk_fma_f32 v[150:151], v[122:123], v[114:115], v[130:131] neg_lo:[0,0,1] neg_hi:[0,0,1]
	v_pk_fma_f32 v[154:155], v[126:127], v[114:115], v[118:119]
	v_pk_mul_f32 v[118:119], v[152:153], v[156:157] op_sel_hi:[1,0]
	v_mul_f32_e32 v122, v124, v190
	v_pk_mul_f32 v[120:121], v[120:121], v[118:119]
	v_mul_f32_e32 v114, v128, v116
	v_mov_b32_e32 v191, v121
	v_mov_b32_e32 v117, v120
	v_pk_mul_f32 v[118:119], v[128:129], v[190:191]
	s_nop 0
	v_pk_fma_f32 v[118:119], v[124:125], v[116:117], v[118:119] neg_lo:[0,0,1] neg_hi:[0,0,1]
	v_mov_b32_e32 v124, v129
	v_pk_mul_f32 v[116:117], v[124:125], v[120:121]
	v_mov_b32_e32 v152, v119
	v_mov_b32_e32 v115, v116
	v_mov_b32_e32 v123, v117
	v_pk_add_f32 v[114:115], v[114:115], v[122:123]
	s_nop 0
	v_mov_b32_e32 v123, v114
	v_mov_b32_e32 v153, v115
	v_add_u32_e32 v222, 0x20, v186
	v_lshlrev_b32_e32 v222, 7, v222
	v_and_b32_e32 v222, 0xfff80, v222
	v_mad_u64_u32 v[220:221], vcc, v222, 1, v[168:169]
	global_load_dwordx4 v[240:243], v[220:221], off offset:16
	global_load_dwordx4 v[236:239], v[220:221], off
	v_add_co_u32_e32 v220, vcc, 0x100000, v220
	s_nop 1
	v_addc_co_u32_e32 v221, vcc, 0, v221, vcc
	global_load_dwordx4 v[248:251], v[220:221], off offset:16
	global_load_dwordx4 v[244:247], v[220:221], off
.LBB0_804:
	v_fmamk_f32 v37, v213, 0x3a800000, v223
	v_mul_f32_e32 v114, 0x4b800000, v37
	v_cmp_gt_f32_e32 vcc, s95, v37
	v_readlane_b32 s24, v254, 27
	v_readlane_b32 s25, v254, 28
	v_cndmask_b32_e32 v37, v37, v114, vcc
	v_rsq_f32_e32 v116, v37
	v_mov_b64_e32 v[114:115], s[24:25]
	v_mad_i64_i32 v[114:115], s[24:25], v25, s82, v[114:115]
	v_mul_f32_e32 v117, 0x45800000, v116
	v_lshl_add_u64 v[114:115], s[20:21], 1, v[114:115]
	v_cndmask_b32_e32 v120, v116, v117, vcc
	v_lshl_add_u64 v[124:125], v[180:181], 1, v[114:115]
	v_cvt_pk_bf16_f32 v114, v144, v145
	v_cvt_pk_bf16_f32 v115, v148, v149
	v_cvt_pk_bf16_f32 v116, v150, v151
	v_cvt_pk_bf16_f32 v117, v118, v152
	v_add_u32_e32 v37, 32, v186
	global_store_dwordx4 v[124:125], v[114:117], off
	s_nop 1
	v_cvt_pk_bf16_f32 v114, v142, v143
	v_cvt_pk_bf16_f32 v115, v146, v147
	v_cvt_pk_bf16_f32 v116, v154, v155
	v_cvt_pk_bf16_f32 v117, v123, v153
	global_store_dwordx4 v[124:125], v[114:117], off offset:64
	v_pk_fma_f32 v[126:127], v[106:107], v[120:121], v[46:47] op_sel_hi:[1,0,1]
	v_fma_f32 v107, v100, v120, v36
	v_mov_b32_e32 v100, v105
	v_pk_fma_f32 v[128:129], v[110:111], v[120:121], v[42:43] op_sel_hi:[1,0,1]
	v_pk_fma_f32 v[134:135], v[102:103], v[120:121], v[22:23] op_sel_hi:[1,0,1]
	v_pk_fma_f32 v[138:139], v[98:99], v[120:121], v[34:35] op_sel_hi:[1,0,1]
	v_fma_f32 v102, v104, v120, v24
	v_pk_fma_f32 v[132:133], v[112:113], v[120:121], v[44:45] op_sel_hi:[1,0,1]
	v_pk_fma_f32 v[130:131], v[108:109], v[120:121], v[48:49] op_sel_hi:[1,0,1]
	s_and_b64 vcc, exec, s[38:39]
	v_pk_fma_f32 v[136:137], v[100:101], v[120:121], v[188:189] op_sel_hi:[1,0,1]
	s_cbranch_vccnz .LBB0_806
	v_pk_mul_f32 v[98:99], v[128:129], v[128:129]
	v_pk_mul_f32 v[100:101], v[132:133], v[132:133]
	v_add_f32_e32 v25, v98, v99
	v_add_f32_e32 v25, v100, v25
	v_pk_mul_f32 v[104:105], v[134:135], v[134:135]
	v_add_f32_e32 v25, v101, v25
	v_add_f32_e32 v25, v104, v25
	v_add_f32_e32 v25, v105, v25
	v_fmac_f32_e32 v25, v102, v102
	v_fmac_f32_e32 v25, v136, v136
	v_pk_mul_f32 v[98:99], v[126:127], v[126:127]
	v_mov_b32_e32 v106, v137
	v_add_f32_e32 v25, v98, v25
	v_add_f32_e32 v25, v99, v25
	v_pk_mul_f32 v[98:99], v[130:131], v[130:131]
	v_readlane_b32 s24, v254, 23
	v_add_f32_e32 v25, v98, v25
	v_add_f32_e32 v25, v99, v25
	v_pk_mul_f32 v[98:99], v[138:139], v[138:139]
	v_mov_b32_e32 v111, v0
	v_add_f32_e32 v25, v98, v25
	v_add_f32_e32 v25, v99, v25
	v_pk_mul_f32 v[98:99], v[106:107], v[106:107]
	v_readlane_b32 s25, v254, 24
	v_add_f32_e32 v25, v99, v25
	v_and_b32_e32 v99, 64, v224
	v_add_f32_e32 v25, v98, v25
	v_xor_b32_e32 v98, 16, v224
	v_add_u32_e32 v99, 64, v99
	v_cmp_lt_i32_e32 vcc, v98, v99
	s_nop 1
	v_cndmask_b32_e32 v98, v224, v98, vcc
	v_lshlrev_b32_e32 v98, 2, v98
	ds_bpermute_b32 v98, v98, v25
	s_waitcnt lgkmcnt(0)
	v_add_f32_e32 v25, v25, v98
	v_xor_b32_e32 v98, 32, v224
	v_cmp_lt_i32_e32 vcc, v98, v99
	s_nop 1
	v_cndmask_b32_e32 v98, v224, v98, vcc
	v_lshlrev_b32_e32 v98, 2, v98
	ds_bpermute_b32 v98, v98, v25
	s_waitcnt lgkmcnt(0)
	v_add_f32_e32 v25, v25, v98
	v_fmamk_f32 v25, v25, 0x3c800000, v223
	v_cmp_gt_f32_e32 vcc, s95, v25
	v_mul_f32_e32 v98, 0x4b800000, v25
	s_nop 0
	v_cndmask_b32_e32 v25, v25, v98, vcc
	v_rsq_f32_e32 v25, v25
	s_nop 0
	v_mul_f32_e32 v98, 0x45800000, v25
	v_cndmask_b32_e32 v140, v25, v98, vcc
	ds_read_b128 v[98:101], v215 offset:16
	ds_read_b128 v[114:117], v215
	v_mul_f32_e32 v25, v102, v140
	ds_read_b128 v[102:105], v215 offset:144
	ds_read_b128 v[118:121], v215 offset:128
	v_pk_mul_f32 v[126:127], v[126:127], v[140:141] op_sel_hi:[1,0]
	v_pk_mul_f32 v[128:129], v[128:129], v[140:141] op_sel_hi:[1,0]
	s_waitcnt lgkmcnt(3)
	v_mul_f32_e32 v100, v100, v25
	v_mul_f32_e32 v25, v107, v140
	s_waitcnt lgkmcnt(1)
	v_mul_f32_e32 v142, v104, v25
	v_lshlrev_b32_e32 v25, 7, v37
	v_and_b32_e32 v110, 0xfff80, v25
	v_lshl_add_u64 v[106:107], s[24:25], 0, v[110:111]
	v_readlane_b32 s24, v254, 25
	v_readlane_b32 s25, v254, 26
	v_lshl_add_u64 v[112:113], v[106:107], 0, v[182:183]
	v_lshl_add_u64 v[110:111], s[24:25], 0, v[110:111]
	v_lshl_add_u64 v[144:145], v[110:111], 0, v[182:183]
	s_waitcnt lgkmcnt(0)
	v_pk_mul_f32 v[118:119], v[118:119], v[126:127]
	v_pk_mul_f32 v[114:115], v[114:115], v[128:129]
	v_mov_b32_e32 v104, v101
	s_waitcnt vmcnt(2)
	v_mov_b64_e32 v[122:123], v[236:237]
	v_mov_b64_e32 v[124:125], v[238:239]
	v_mov_b64_e32 v[106:107], v[240:241]
	v_mov_b64_e32 v[108:109], v[242:243]
	v_mov_b64_e32 v[144:145], v[244:245]
	v_mov_b64_e32 v[146:147], v[246:247]
	v_mov_b64_e32 v[110:111], v[248:249]
	v_mov_b64_e32 v[112:113], v[250:251]
	v_pk_mul_f32 v[126:127], v[144:145], v[118:119]
	v_pk_mul_f32 v[118:119], v[122:123], v[118:119]
	v_pk_fma_f32 v[128:129], v[122:123], v[114:115], v[126:127] neg_lo:[0,0,1] neg_hi:[0,0,1]
	v_pk_fma_f32 v[126:127], v[144:145], v[114:115], v[118:119]
	v_pk_mul_f32 v[114:115], v[132:133], v[140:141] op_sel_hi:[1,0]
	s_nop 0
	v_pk_mul_f32 v[114:115], v[116:117], v[114:115]
	v_pk_mul_f32 v[116:117], v[130:131], v[140:141] op_sel_hi:[1,0]
	s_nop 0
	v_pk_mul_f32 v[116:117], v[120:121], v[116:117]
	s_nop 0
	v_pk_mul_f32 v[118:119], v[146:147], v[116:117]
	v_pk_mul_f32 v[116:117], v[124:125], v[116:117]
	v_pk_fma_f32 v[132:133], v[124:125], v[114:115], v[118:119] neg_lo:[0,0,1] neg_hi:[0,0,1]
	v_pk_fma_f32 v[130:131], v[146:147], v[114:115], v[116:117]
	v_pk_mul_f32 v[114:115], v[134:135], v[140:141] op_sel_hi:[1,0]
	s_nop 0
	v_pk_mul_f32 v[98:99], v[98:99], v[114:115]
	v_pk_mul_f32 v[114:115], v[138:139], v[140:141] op_sel_hi:[1,0]
	s_nop 0
	v_pk_mul_f32 v[102:103], v[102:103], v[114:115]
	s_nop 0
	v_pk_mul_f32 v[114:115], v[110:111], v[102:103]
	v_pk_mul_f32 v[102:103], v[106:107], v[102:103]
	v_pk_fma_f32 v[134:135], v[106:107], v[98:99], v[114:115] neg_lo:[0,0,1] neg_hi:[0,0,1]
	v_pk_fma_f32 v[138:139], v[110:111], v[98:99], v[102:103]
	v_pk_mul_f32 v[102:103], v[136:137], v[140:141] op_sel_hi:[1,0]
	v_mul_f32_e32 v106, v108, v142
	v_pk_mul_f32 v[104:105], v[104:105], v[102:103]
	v_mul_f32_e32 v98, v112, v100
	v_mov_b32_e32 v143, v105
	v_mov_b32_e32 v101, v104
	v_pk_mul_f32 v[102:103], v[112:113], v[142:143]
	s_nop 0
	v_pk_fma_f32 v[102:103], v[108:109], v[100:101], v[102:103] neg_lo:[0,0,1] neg_hi:[0,0,1]
	v_mov_b32_e32 v108, v113
	v_pk_mul_f32 v[100:101], v[108:109], v[104:105]
	v_mov_b32_e32 v136, v103
	v_mov_b32_e32 v99, v100
	v_mov_b32_e32 v107, v101
	v_pk_add_f32 v[98:99], v[98:99], v[106:107]
	s_nop 0
	v_mov_b32_e32 v107, v98
	v_mov_b32_e32 v137, v99
	v_add_u32_e32 v222, 0x30, v186
	v_lshlrev_b32_e32 v222, 7, v222
	v_and_b32_e32 v222, 0xfff80, v222
	v_mad_u64_u32 v[220:221], vcc, v222, 1, v[168:169]
	global_load_dwordx4 v[240:243], v[220:221], off offset:16
	global_load_dwordx4 v[236:239], v[220:221], off
	v_add_co_u32_e32 v220, vcc, 0x100000, v220
	s_nop 1
	v_addc_co_u32_e32 v221, vcc, 0, v221, vcc
	global_load_dwordx4 v[248:251], v[220:221], off offset:16
	global_load_dwordx4 v[244:247], v[220:221], off
.LBB0_806:
	v_fmamk_f32 v25, v212, 0x3a800000, v223
	v_mul_f32_e32 v98, 0x4b800000, v25
	v_cmp_gt_f32_e32 vcc, s95, v25
	v_readlane_b32 s24, v254, 27
	v_readlane_b32 s25, v254, 28
	v_cndmask_b32_e32 v25, v25, v98, vcc
	v_rsq_f32_e32 v100, v25
	v_mov_b64_e32 v[98:99], s[24:25]
	v_mad_i64_i32 v[98:99], s[24:25], v37, s82, v[98:99]
	v_mul_f32_e32 v101, 0x45800000, v100
	v_lshl_add_u64 v[98:99], s[20:21], 1, v[98:99]
	v_cndmask_b32_e32 v104, v100, v101, vcc
	v_lshl_add_u64 v[108:109], v[180:181], 1, v[98:99]
	v_cvt_pk_bf16_f32 v98, v128, v129
	v_cvt_pk_bf16_f32 v99, v132, v133
	v_cvt_pk_bf16_f32 v100, v134, v135
	v_cvt_pk_bf16_f32 v101, v102, v136
	v_add_u32_e32 v25, 48, v186
	global_store_dwordx4 v[108:109], v[98:101], off
	s_nop 1
	v_cvt_pk_bf16_f32 v98, v126, v127
	v_cvt_pk_bf16_f32 v99, v130, v131
	v_cvt_pk_bf16_f32 v100, v138, v139
	v_cvt_pk_bf16_f32 v101, v107, v137
	global_store_dwordx4 v[108:109], v[98:101], off offset:64
	v_pk_fma_f32 v[110:111], v[90:91], v[104:105], v[46:47] op_sel_hi:[1,0,1]
	v_fma_f32 v91, v84, v104, v36
	v_mov_b32_e32 v84, v89
	v_pk_fma_f32 v[112:113], v[94:95], v[104:105], v[42:43] op_sel_hi:[1,0,1]
	v_pk_fma_f32 v[118:119], v[86:87], v[104:105], v[22:23] op_sel_hi:[1,0,1]
	v_pk_fma_f32 v[122:123], v[82:83], v[104:105], v[34:35] op_sel_hi:[1,0,1]
	v_fma_f32 v86, v88, v104, v24
	v_pk_fma_f32 v[116:117], v[96:97], v[104:105], v[44:45] op_sel_hi:[1,0,1]
	v_pk_fma_f32 v[114:115], v[92:93], v[104:105], v[48:49] op_sel_hi:[1,0,1]
	s_and_b64 vcc, exec, s[38:39]
	v_pk_fma_f32 v[120:121], v[84:85], v[104:105], v[188:189] op_sel_hi:[1,0,1]
	s_cbranch_vccnz .LBB0_808
	v_pk_mul_f32 v[82:83], v[112:113], v[112:113]
	v_pk_mul_f32 v[84:85], v[116:117], v[116:117]
	v_add_f32_e32 v37, v82, v83
	v_add_f32_e32 v37, v84, v37
	v_pk_mul_f32 v[88:89], v[118:119], v[118:119]
	v_add_f32_e32 v37, v85, v37
	v_add_f32_e32 v37, v88, v37
	v_add_f32_e32 v37, v89, v37
	v_fmac_f32_e32 v37, v86, v86
	v_fmac_f32_e32 v37, v120, v120
	v_pk_mul_f32 v[82:83], v[110:111], v[110:111]
	v_mov_b32_e32 v90, v121
	v_add_f32_e32 v37, v82, v37
	v_add_f32_e32 v37, v83, v37
	v_pk_mul_f32 v[82:83], v[114:115], v[114:115]
	v_readlane_b32 s24, v254, 23
	v_add_f32_e32 v37, v82, v37
	v_add_f32_e32 v37, v83, v37
	v_pk_mul_f32 v[82:83], v[122:123], v[122:123]
	v_mov_b32_e32 v95, v0
	v_add_f32_e32 v37, v82, v37
	v_add_f32_e32 v37, v83, v37
	v_pk_mul_f32 v[82:83], v[90:91], v[90:91]
	v_readlane_b32 s25, v254, 24
	v_add_f32_e32 v37, v83, v37
	v_and_b32_e32 v83, 64, v224
	v_add_f32_e32 v37, v82, v37
	v_xor_b32_e32 v82, 16, v224
	v_add_u32_e32 v83, 64, v83
	v_cmp_lt_i32_e32 vcc, v82, v83
	s_nop 1
	v_cndmask_b32_e32 v82, v224, v82, vcc
	v_lshlrev_b32_e32 v82, 2, v82
	ds_bpermute_b32 v82, v82, v37
	s_waitcnt lgkmcnt(0)
	v_add_f32_e32 v37, v37, v82
	v_xor_b32_e32 v82, 32, v224
	v_cmp_lt_i32_e32 vcc, v82, v83
	s_nop 1
	v_cndmask_b32_e32 v82, v224, v82, vcc
	v_lshlrev_b32_e32 v82, 2, v82
	ds_bpermute_b32 v82, v82, v37
	s_waitcnt lgkmcnt(0)
	v_add_f32_e32 v37, v37, v82
	v_fmamk_f32 v37, v37, 0x3c800000, v223
	v_cmp_gt_f32_e32 vcc, s95, v37
	v_mul_f32_e32 v82, 0x4b800000, v37
	s_nop 0
	v_cndmask_b32_e32 v37, v37, v82, vcc
	v_rsq_f32_e32 v37, v37
	s_nop 0
	v_mul_f32_e32 v82, 0x45800000, v37
	v_cndmask_b32_e32 v124, v37, v82, vcc
	ds_read_b128 v[82:85], v215 offset:16
	ds_read_b128 v[98:101], v215
	v_mul_f32_e32 v37, v86, v124
	ds_read_b128 v[86:89], v215 offset:144
	ds_read_b128 v[102:105], v215 offset:128
	v_pk_mul_f32 v[110:111], v[110:111], v[124:125] op_sel_hi:[1,0]
	v_pk_mul_f32 v[112:113], v[112:113], v[124:125] op_sel_hi:[1,0]
	s_waitcnt lgkmcnt(3)
	v_mul_f32_e32 v84, v84, v37
	v_mul_f32_e32 v37, v91, v124
	s_waitcnt lgkmcnt(1)
	v_mul_f32_e32 v126, v88, v37
	v_lshlrev_b32_e32 v37, 7, v25
	v_and_b32_e32 v94, 0xfff80, v37
	v_lshl_add_u64 v[90:91], s[24:25], 0, v[94:95]
	v_readlane_b32 s24, v254, 25
	v_readlane_b32 s25, v254, 26
	v_lshl_add_u64 v[96:97], v[90:91], 0, v[182:183]
	v_lshl_add_u64 v[94:95], s[24:25], 0, v[94:95]
	v_lshl_add_u64 v[128:129], v[94:95], 0, v[182:183]
	s_waitcnt lgkmcnt(0)
	v_pk_mul_f32 v[102:103], v[102:103], v[110:111]
	v_pk_mul_f32 v[98:99], v[98:99], v[112:113]
	v_mov_b32_e32 v88, v85
	s_waitcnt vmcnt(2)
	v_mov_b64_e32 v[106:107], v[236:237]
	v_mov_b64_e32 v[108:109], v[238:239]
	v_mov_b64_e32 v[90:91], v[240:241]
	v_mov_b64_e32 v[92:93], v[242:243]
	v_mov_b64_e32 v[128:129], v[244:245]
	v_mov_b64_e32 v[130:131], v[246:247]
	v_mov_b64_e32 v[94:95], v[248:249]
	v_mov_b64_e32 v[96:97], v[250:251]
	v_pk_mul_f32 v[110:111], v[128:129], v[102:103]
	v_pk_mul_f32 v[102:103], v[106:107], v[102:103]
	v_pk_fma_f32 v[112:113], v[106:107], v[98:99], v[110:111] neg_lo:[0,0,1] neg_hi:[0,0,1]
	v_pk_fma_f32 v[110:111], v[128:129], v[98:99], v[102:103]
	v_pk_mul_f32 v[98:99], v[116:117], v[124:125] op_sel_hi:[1,0]
	s_nop 0
	v_pk_mul_f32 v[98:99], v[100:101], v[98:99]
	v_pk_mul_f32 v[100:101], v[114:115], v[124:125] op_sel_hi:[1,0]
	s_nop 0
	v_pk_mul_f32 v[100:101], v[104:105], v[100:101]
	s_nop 0
	v_pk_mul_f32 v[102:103], v[130:131], v[100:101]
	v_pk_mul_f32 v[100:101], v[108:109], v[100:101]
	v_pk_fma_f32 v[116:117], v[108:109], v[98:99], v[102:103] neg_lo:[0,0,1] neg_hi:[0,0,1]
	v_pk_fma_f32 v[114:115], v[130:131], v[98:99], v[100:101]
	v_pk_mul_f32 v[98:99], v[118:119], v[124:125] op_sel_hi:[1,0]
	s_nop 0
	v_pk_mul_f32 v[82:83], v[82:83], v[98:99]
	v_pk_mul_f32 v[98:99], v[122:123], v[124:125] op_sel_hi:[1,0]
	s_nop 0
	v_pk_mul_f32 v[86:87], v[86:87], v[98:99]
	s_nop 0
	v_pk_mul_f32 v[98:99], v[94:95], v[86:87]
	v_pk_mul_f32 v[86:87], v[90:91], v[86:87]
	v_pk_fma_f32 v[118:119], v[90:91], v[82:83], v[98:99] neg_lo:[0,0,1] neg_hi:[0,0,1]
	v_pk_fma_f32 v[122:123], v[94:95], v[82:83], v[86:87]
	v_pk_mul_f32 v[86:87], v[120:121], v[124:125] op_sel_hi:[1,0]
	v_mul_f32_e32 v90, v92, v126
	v_pk_mul_f32 v[88:89], v[88:89], v[86:87]
	v_mul_f32_e32 v82, v96, v84
	v_mov_b32_e32 v127, v89
	v_mov_b32_e32 v85, v88
	v_pk_mul_f32 v[86:87], v[96:97], v[126:127]
	s_nop 0
	v_pk_fma_f32 v[86:87], v[92:93], v[84:85], v[86:87] neg_lo:[0,0,1] neg_hi:[0,0,1]
	v_mov_b32_e32 v92, v97
	v_pk_mul_f32 v[84:85], v[92:93], v[88:89]
	v_mov_b32_e32 v120, v87
	v_mov_b32_e32 v83, v84
	v_mov_b32_e32 v91, v85
	v_pk_add_f32 v[82:83], v[82:83], v[90:91]
	s_nop 0
	v_mov_b32_e32 v91, v82
	v_mov_b32_e32 v121, v83
	v_add_u32_e32 v222, 0x80, v186
	v_lshlrev_b32_e32 v222, 7, v222
	v_and_b32_e32 v222, 0xfff80, v222
	v_mad_u64_u32 v[220:221], vcc, v222, 1, v[168:169]
	global_load_dwordx4 v[240:243], v[220:221], off offset:16
	global_load_dwordx4 v[236:239], v[220:221], off
	v_add_co_u32_e32 v220, vcc, 0x100000, v220
	s_nop 1
	v_addc_co_u32_e32 v221, vcc, 0, v221, vcc
	global_load_dwordx4 v[248:251], v[220:221], off offset:16
	global_load_dwordx4 v[244:247], v[220:221], off
.LBB0_808:
	v_fmamk_f32 v37, v211, 0x3a800000, v223
	v_mul_f32_e32 v82, 0x4b800000, v37
	v_cmp_gt_f32_e32 vcc, s95, v37
	v_readlane_b32 s24, v254, 27
	v_readlane_b32 s25, v254, 28
	v_cndmask_b32_e32 v37, v37, v82, vcc
	v_rsq_f32_e32 v84, v37
	v_mov_b64_e32 v[82:83], s[24:25]
	v_mad_i64_i32 v[82:83], s[24:25], v25, s82, v[82:83]
	v_mul_f32_e32 v85, 0x45800000, v84
	v_lshl_add_u64 v[82:83], s[20:21], 1, v[82:83]
	v_cndmask_b32_e32 v88, v84, v85, vcc
	v_lshl_add_u64 v[92:93], v[180:181], 1, v[82:83]
	v_cvt_pk_bf16_f32 v82, v112, v113
	v_cvt_pk_bf16_f32 v83, v116, v117
	v_cvt_pk_bf16_f32 v84, v118, v119
	v_cvt_pk_bf16_f32 v85, v86, v120
	v_add_u32_e32 v37, 0x80, v186
	global_store_dwordx4 v[92:93], v[82:85], off
	s_nop 1
	v_cvt_pk_bf16_f32 v82, v110, v111
	v_cvt_pk_bf16_f32 v83, v114, v115
	v_cvt_pk_bf16_f32 v84, v122, v123
	v_cvt_pk_bf16_f32 v85, v91, v121
	global_store_dwordx4 v[92:93], v[82:85], off offset:64
	v_pk_fma_f32 v[94:95], v[74:75], v[88:89], v[46:47] op_sel_hi:[1,0,1]
	v_fma_f32 v75, v68, v88, v36
	v_mov_b32_e32 v68, v73
	v_pk_fma_f32 v[96:97], v[78:79], v[88:89], v[42:43] op_sel_hi:[1,0,1]
	v_pk_fma_f32 v[102:103], v[70:71], v[88:89], v[22:23] op_sel_hi:[1,0,1]
	v_pk_fma_f32 v[106:107], v[66:67], v[88:89], v[34:35] op_sel_hi:[1,0,1]
	v_fma_f32 v70, v72, v88, v24
	v_pk_fma_f32 v[100:101], v[80:81], v[88:89], v[44:45] op_sel_hi:[1,0,1]
	v_pk_fma_f32 v[98:99], v[76:77], v[88:89], v[48:49] op_sel_hi:[1,0,1]
	s_and_b64 vcc, exec, s[38:39]
	v_pk_fma_f32 v[104:105], v[68:69], v[88:89], v[188:189] op_sel_hi:[1,0,1]
	s_cbranch_vccnz .LBB0_810
	v_pk_mul_f32 v[66:67], v[96:97], v[96:97]
	v_pk_mul_f32 v[68:69], v[100:101], v[100:101]
	v_add_f32_e32 v25, v66, v67
	v_add_f32_e32 v25, v68, v25
	v_pk_mul_f32 v[72:73], v[102:103], v[102:103]
	v_add_f32_e32 v25, v69, v25
	v_add_f32_e32 v25, v72, v25
	v_add_f32_e32 v25, v73, v25
	v_fmac_f32_e32 v25, v70, v70
	v_fmac_f32_e32 v25, v104, v104
	v_pk_mul_f32 v[66:67], v[94:95], v[94:95]
	v_mov_b32_e32 v74, v105
	v_add_f32_e32 v25, v66, v25
	v_add_f32_e32 v25, v67, v25
	v_pk_mul_f32 v[66:67], v[98:99], v[98:99]
	v_readlane_b32 s24, v254, 23
	v_add_f32_e32 v25, v66, v25
	v_add_f32_e32 v25, v67, v25
	v_pk_mul_f32 v[66:67], v[106:107], v[106:107]
	v_mov_b32_e32 v79, v0
	v_add_f32_e32 v25, v66, v25
	v_add_f32_e32 v25, v67, v25
	v_pk_mul_f32 v[66:67], v[74:75], v[74:75]
	v_readlane_b32 s25, v254, 24
	v_add_f32_e32 v25, v67, v25
	v_and_b32_e32 v67, 64, v224
	v_add_f32_e32 v25, v66, v25
	v_xor_b32_e32 v66, 16, v224
	v_add_u32_e32 v67, 64, v67
	v_cmp_lt_i32_e32 vcc, v66, v67
	s_nop 1
	v_cndmask_b32_e32 v66, v224, v66, vcc
	v_lshlrev_b32_e32 v66, 2, v66
	ds_bpermute_b32 v66, v66, v25
	s_waitcnt lgkmcnt(0)
	v_add_f32_e32 v25, v25, v66
	v_xor_b32_e32 v66, 32, v224
	v_cmp_lt_i32_e32 vcc, v66, v67
	s_nop 1
	v_cndmask_b32_e32 v66, v224, v66, vcc
	v_lshlrev_b32_e32 v66, 2, v66
	ds_bpermute_b32 v66, v66, v25
	s_waitcnt lgkmcnt(0)
	v_add_f32_e32 v25, v25, v66
	v_fmamk_f32 v25, v25, 0x3c800000, v223
	v_cmp_gt_f32_e32 vcc, s95, v25
	v_mul_f32_e32 v66, 0x4b800000, v25
	s_nop 0
	v_cndmask_b32_e32 v25, v25, v66, vcc
	v_rsq_f32_e32 v25, v25
	s_nop 0
	v_mul_f32_e32 v66, 0x45800000, v25
	v_cndmask_b32_e32 v108, v25, v66, vcc
	ds_read_b128 v[66:69], v215 offset:16
	ds_read_b128 v[82:85], v215
	v_mul_f32_e32 v25, v70, v108
	ds_read_b128 v[70:73], v215 offset:144
	ds_read_b128 v[86:89], v215 offset:128
	v_pk_mul_f32 v[94:95], v[94:95], v[108:109] op_sel_hi:[1,0]
	v_pk_mul_f32 v[96:97], v[96:97], v[108:109] op_sel_hi:[1,0]
	s_waitcnt lgkmcnt(3)
	v_mul_f32_e32 v68, v68, v25
	v_mul_f32_e32 v25, v75, v108
	s_waitcnt lgkmcnt(1)
	v_mul_f32_e32 v110, v72, v25
	v_lshlrev_b32_e32 v25, 7, v37
	v_and_b32_e32 v78, 0xfff80, v25
	v_lshl_add_u64 v[74:75], s[24:25], 0, v[78:79]
	v_readlane_b32 s24, v254, 25
	v_readlane_b32 s25, v254, 26
	v_lshl_add_u64 v[80:81], v[74:75], 0, v[182:183]
	v_lshl_add_u64 v[78:79], s[24:25], 0, v[78:79]
	v_lshl_add_u64 v[112:113], v[78:79], 0, v[182:183]
	s_waitcnt lgkmcnt(0)
	v_pk_mul_f32 v[86:87], v[86:87], v[94:95]
	v_pk_mul_f32 v[82:83], v[82:83], v[96:97]
	v_mov_b32_e32 v72, v69
	s_waitcnt vmcnt(2)
	v_mov_b64_e32 v[90:91], v[236:237]
	v_mov_b64_e32 v[92:93], v[238:239]
	v_mov_b64_e32 v[74:75], v[240:241]
	v_mov_b64_e32 v[76:77], v[242:243]
	v_mov_b64_e32 v[112:113], v[244:245]
	v_mov_b64_e32 v[114:115], v[246:247]
	v_mov_b64_e32 v[78:79], v[248:249]
	v_mov_b64_e32 v[80:81], v[250:251]
	v_pk_mul_f32 v[94:95], v[112:113], v[86:87]
	v_pk_mul_f32 v[86:87], v[90:91], v[86:87]
	v_pk_fma_f32 v[96:97], v[90:91], v[82:83], v[94:95] neg_lo:[0,0,1] neg_hi:[0,0,1]
	v_pk_fma_f32 v[94:95], v[112:113], v[82:83], v[86:87]
	v_pk_mul_f32 v[82:83], v[100:101], v[108:109] op_sel_hi:[1,0]
	s_nop 0
	v_pk_mul_f32 v[82:83], v[84:85], v[82:83]
	v_pk_mul_f32 v[84:85], v[98:99], v[108:109] op_sel_hi:[1,0]
	s_nop 0
	v_pk_mul_f32 v[84:85], v[88:89], v[84:85]
	s_nop 0
	v_pk_mul_f32 v[86:87], v[114:115], v[84:85]
	v_pk_mul_f32 v[84:85], v[92:93], v[84:85]
	v_pk_fma_f32 v[100:101], v[92:93], v[82:83], v[86:87] neg_lo:[0,0,1] neg_hi:[0,0,1]
	v_pk_fma_f32 v[98:99], v[114:115], v[82:83], v[84:85]
	v_pk_mul_f32 v[82:83], v[102:103], v[108:109] op_sel_hi:[1,0]
	s_nop 0
	v_pk_mul_f32 v[66:67], v[66:67], v[82:83]
	v_pk_mul_f32 v[82:83], v[106:107], v[108:109] op_sel_hi:[1,0]
	s_nop 0
	v_pk_mul_f32 v[70:71], v[70:71], v[82:83]
	s_nop 0
	v_pk_mul_f32 v[82:83], v[78:79], v[70:71]
	v_pk_mul_f32 v[70:71], v[74:75], v[70:71]
	v_pk_fma_f32 v[102:103], v[74:75], v[66:67], v[82:83] neg_lo:[0,0,1] neg_hi:[0,0,1]
	v_pk_fma_f32 v[106:107], v[78:79], v[66:67], v[70:71]
	v_pk_mul_f32 v[70:71], v[104:105], v[108:109] op_sel_hi:[1,0]
	v_mul_f32_e32 v74, v76, v110
	v_pk_mul_f32 v[72:73], v[72:73], v[70:71]
	v_mul_f32_e32 v66, v80, v68
	v_mov_b32_e32 v111, v73
	v_mov_b32_e32 v69, v72
	v_pk_mul_f32 v[70:71], v[80:81], v[110:111]
	s_nop 0
	v_pk_fma_f32 v[70:71], v[76:77], v[68:69], v[70:71] neg_lo:[0,0,1] neg_hi:[0,0,1]
	v_mov_b32_e32 v76, v81
	v_pk_mul_f32 v[68:69], v[76:77], v[72:73]
	v_mov_b32_e32 v104, v71
	v_mov_b32_e32 v67, v68
	v_mov_b32_e32 v75, v69
	v_pk_add_f32 v[66:67], v[66:67], v[74:75]
	s_nop 0
	v_mov_b32_e32 v75, v66
	v_mov_b32_e32 v105, v67
	v_add_u32_e32 v222, 0x90, v186
	v_lshlrev_b32_e32 v222, 7, v222
	v_and_b32_e32 v222, 0xfff80, v222
	v_mad_u64_u32 v[220:221], vcc, v222, 1, v[168:169]
	global_load_dwordx4 v[240:243], v[220:221], off offset:16
	global_load_dwordx4 v[236:239], v[220:221], off
	v_add_co_u32_e32 v220, vcc, 0x100000, v220
	s_nop 1
	v_addc_co_u32_e32 v221, vcc, 0, v221, vcc
	global_load_dwordx4 v[248:251], v[220:221], off offset:16
	global_load_dwordx4 v[244:247], v[220:221], off
.LBB0_810:
	v_fmamk_f32 v25, v210, 0x3a800000, v223
	v_mul_f32_e32 v66, 0x4b800000, v25
	v_cmp_gt_f32_e32 vcc, s95, v25
	v_readlane_b32 s24, v254, 27
	v_readlane_b32 s25, v254, 28
	v_cndmask_b32_e32 v25, v25, v66, vcc
	v_rsq_f32_e32 v68, v25
	v_mov_b64_e32 v[66:67], s[24:25]
	v_mad_i64_i32 v[66:67], s[24:25], v37, s82, v[66:67]
	v_mul_f32_e32 v69, 0x45800000, v68
	v_lshl_add_u64 v[66:67], s[20:21], 1, v[66:67]
	v_cndmask_b32_e32 v72, v68, v69, vcc
	v_lshl_add_u64 v[76:77], v[180:181], 1, v[66:67]
	v_cvt_pk_bf16_f32 v66, v96, v97
	v_cvt_pk_bf16_f32 v67, v100, v101
	v_cvt_pk_bf16_f32 v68, v102, v103
	v_cvt_pk_bf16_f32 v69, v70, v104
	v_add_u32_e32 v25, 0x90, v186
	global_store_dwordx4 v[76:77], v[66:69], off
	s_nop 1
	v_cvt_pk_bf16_f32 v66, v94, v95
	v_cvt_pk_bf16_f32 v67, v98, v99
	v_cvt_pk_bf16_f32 v68, v106, v107
	v_cvt_pk_bf16_f32 v69, v75, v105
	global_store_dwordx4 v[76:77], v[66:69], off offset:64
	v_pk_fma_f32 v[78:79], v[58:59], v[72:73], v[46:47] op_sel_hi:[1,0,1]
	v_fma_f32 v59, v52, v72, v36
	v_mov_b32_e32 v52, v57
	v_pk_fma_f32 v[80:81], v[62:63], v[72:73], v[42:43] op_sel_hi:[1,0,1]
	v_pk_fma_f32 v[86:87], v[54:55], v[72:73], v[22:23] op_sel_hi:[1,0,1]
	v_pk_fma_f32 v[90:91], v[50:51], v[72:73], v[34:35] op_sel_hi:[1,0,1]
	v_fma_f32 v54, v56, v72, v24
	v_pk_fma_f32 v[84:85], v[64:65], v[72:73], v[44:45] op_sel_hi:[1,0,1]
	v_pk_fma_f32 v[82:83], v[60:61], v[72:73], v[48:49] op_sel_hi:[1,0,1]
	s_and_b64 vcc, exec, s[38:39]
	v_pk_fma_f32 v[88:89], v[52:53], v[72:73], v[188:189] op_sel_hi:[1,0,1]
	s_cbranch_vccnz .LBB0_812
	v_pk_mul_f32 v[50:51], v[80:81], v[80:81]
	v_pk_mul_f32 v[52:53], v[84:85], v[84:85]
	v_add_f32_e32 v37, v50, v51
	v_add_f32_e32 v37, v52, v37
	v_pk_mul_f32 v[56:57], v[86:87], v[86:87]
	v_add_f32_e32 v37, v53, v37
	v_add_f32_e32 v37, v56, v37
	v_add_f32_e32 v37, v57, v37
	v_fmac_f32_e32 v37, v54, v54
	v_fmac_f32_e32 v37, v88, v88
	v_pk_mul_f32 v[50:51], v[78:79], v[78:79]
	v_mov_b32_e32 v58, v89
	v_add_f32_e32 v37, v50, v37
	v_add_f32_e32 v37, v51, v37
	v_pk_mul_f32 v[50:51], v[82:83], v[82:83]
	v_readlane_b32 s24, v254, 23
	v_add_f32_e32 v37, v50, v37
	v_add_f32_e32 v37, v51, v37
	v_pk_mul_f32 v[50:51], v[90:91], v[90:91]
	v_mov_b32_e32 v63, v0
	v_add_f32_e32 v37, v50, v37
	v_add_f32_e32 v37, v51, v37
	v_pk_mul_f32 v[50:51], v[58:59], v[58:59]
	v_readlane_b32 s25, v254, 24
	v_add_f32_e32 v37, v51, v37
	v_and_b32_e32 v51, 64, v224
	v_add_f32_e32 v37, v50, v37
	v_xor_b32_e32 v50, 16, v224
	v_add_u32_e32 v51, 64, v51
	v_cmp_lt_i32_e32 vcc, v50, v51
	s_nop 1
	v_cndmask_b32_e32 v50, v224, v50, vcc
	v_lshlrev_b32_e32 v50, 2, v50
	ds_bpermute_b32 v50, v50, v37
	s_waitcnt lgkmcnt(0)
	v_add_f32_e32 v37, v37, v50
	v_xor_b32_e32 v50, 32, v224
	v_cmp_lt_i32_e32 vcc, v50, v51
	s_nop 1
	v_cndmask_b32_e32 v50, v224, v50, vcc
	v_lshlrev_b32_e32 v50, 2, v50
	ds_bpermute_b32 v50, v50, v37
	s_waitcnt lgkmcnt(0)
	v_add_f32_e32 v37, v37, v50
	v_fmamk_f32 v37, v37, 0x3c800000, v223
	v_cmp_gt_f32_e32 vcc, s95, v37
	v_mul_f32_e32 v50, 0x4b800000, v37
	s_nop 0
	v_cndmask_b32_e32 v37, v37, v50, vcc
	v_rsq_f32_e32 v37, v37
	s_nop 0
	v_mul_f32_e32 v50, 0x45800000, v37
	v_cndmask_b32_e32 v92, v37, v50, vcc
	ds_read_b128 v[50:53], v215 offset:16
	ds_read_b128 v[66:69], v215
	v_mul_f32_e32 v37, v54, v92
	ds_read_b128 v[54:57], v215 offset:144
	ds_read_b128 v[70:73], v215 offset:128
	v_pk_mul_f32 v[78:79], v[78:79], v[92:93] op_sel_hi:[1,0]
	v_pk_mul_f32 v[80:81], v[80:81], v[92:93] op_sel_hi:[1,0]
	s_waitcnt lgkmcnt(3)
	v_mul_f32_e32 v52, v52, v37
	v_mul_f32_e32 v37, v59, v92
	s_waitcnt lgkmcnt(1)
	v_mul_f32_e32 v94, v56, v37
	v_lshlrev_b32_e32 v37, 7, v25
	v_and_b32_e32 v62, 0xfff80, v37
	v_lshl_add_u64 v[58:59], s[24:25], 0, v[62:63]
	v_readlane_b32 s24, v254, 25
	v_readlane_b32 s25, v254, 26
	v_lshl_add_u64 v[64:65], v[58:59], 0, v[182:183]
	v_lshl_add_u64 v[62:63], s[24:25], 0, v[62:63]
	v_lshl_add_u64 v[96:97], v[62:63], 0, v[182:183]
	s_waitcnt lgkmcnt(0)
	v_pk_mul_f32 v[70:71], v[70:71], v[78:79]
	v_pk_mul_f32 v[66:67], v[66:67], v[80:81]
	v_mov_b32_e32 v56, v53
	s_waitcnt vmcnt(2)
	v_mov_b64_e32 v[74:75], v[236:237]
	v_mov_b64_e32 v[76:77], v[238:239]
	v_mov_b64_e32 v[58:59], v[240:241]
	v_mov_b64_e32 v[60:61], v[242:243]
	v_mov_b64_e32 v[96:97], v[244:245]
	v_mov_b64_e32 v[98:99], v[246:247]
	v_mov_b64_e32 v[62:63], v[248:249]
	v_mov_b64_e32 v[64:65], v[250:251]
	v_pk_mul_f32 v[78:79], v[96:97], v[70:71]
	v_pk_mul_f32 v[70:71], v[74:75], v[70:71]
	v_pk_fma_f32 v[80:81], v[74:75], v[66:67], v[78:79] neg_lo:[0,0,1] neg_hi:[0,0,1]
	v_pk_fma_f32 v[78:79], v[96:97], v[66:67], v[70:71]
	v_pk_mul_f32 v[66:67], v[84:85], v[92:93] op_sel_hi:[1,0]
	s_nop 0
	v_pk_mul_f32 v[66:67], v[68:69], v[66:67]
	v_pk_mul_f32 v[68:69], v[82:83], v[92:93] op_sel_hi:[1,0]
	s_nop 0
	v_pk_mul_f32 v[68:69], v[72:73], v[68:69]
	s_nop 0
	v_pk_mul_f32 v[70:71], v[98:99], v[68:69]
	v_pk_mul_f32 v[68:69], v[76:77], v[68:69]
	v_pk_fma_f32 v[84:85], v[76:77], v[66:67], v[70:71] neg_lo:[0,0,1] neg_hi:[0,0,1]
	v_pk_fma_f32 v[82:83], v[98:99], v[66:67], v[68:69]
	v_pk_mul_f32 v[66:67], v[86:87], v[92:93] op_sel_hi:[1,0]
	s_nop 0
	v_pk_mul_f32 v[50:51], v[50:51], v[66:67]
	v_pk_mul_f32 v[66:67], v[90:91], v[92:93] op_sel_hi:[1,0]
	s_nop 0
	v_pk_mul_f32 v[54:55], v[54:55], v[66:67]
	s_nop 0
	v_pk_mul_f32 v[66:67], v[62:63], v[54:55]
	v_pk_mul_f32 v[54:55], v[58:59], v[54:55]
	v_pk_fma_f32 v[86:87], v[58:59], v[50:51], v[66:67] neg_lo:[0,0,1] neg_hi:[0,0,1]
	v_pk_fma_f32 v[90:91], v[62:63], v[50:51], v[54:55]
	v_pk_mul_f32 v[54:55], v[88:89], v[92:93] op_sel_hi:[1,0]
	v_mul_f32_e32 v58, v60, v94
	v_pk_mul_f32 v[56:57], v[56:57], v[54:55]
	v_mul_f32_e32 v50, v64, v52
	v_mov_b32_e32 v95, v57
	v_mov_b32_e32 v53, v56
	v_pk_mul_f32 v[54:55], v[64:65], v[94:95]
	s_nop 0
	v_pk_fma_f32 v[54:55], v[60:61], v[52:53], v[54:55] neg_lo:[0,0,1] neg_hi:[0,0,1]
	v_mov_b32_e32 v60, v65
	v_pk_mul_f32 v[52:53], v[60:61], v[56:57]
	v_mov_b32_e32 v88, v55
	v_mov_b32_e32 v51, v52
	v_mov_b32_e32 v59, v53
	v_pk_add_f32 v[50:51], v[50:51], v[58:59]
	s_nop 0
	v_mov_b32_e32 v59, v50
	v_mov_b32_e32 v89, v51
	v_add_u32_e32 v222, 0xa0, v186
	v_lshlrev_b32_e32 v222, 7, v222
	v_and_b32_e32 v222, 0xfff80, v222
	v_mad_u64_u32 v[220:221], vcc, v222, 1, v[168:169]
	global_load_dwordx4 v[240:243], v[220:221], off offset:16
	global_load_dwordx4 v[236:239], v[220:221], off
	v_add_co_u32_e32 v220, vcc, 0x100000, v220
	s_nop 1
	v_addc_co_u32_e32 v221, vcc, 0, v221, vcc
	global_load_dwordx4 v[248:251], v[220:221], off offset:16
	global_load_dwordx4 v[244:247], v[220:221], off
.LBB0_812:
	v_fmamk_f32 v37, v209, 0x3a800000, v223
	v_mul_f32_e32 v50, 0x4b800000, v37
	v_cmp_gt_f32_e32 vcc, s95, v37
	v_readlane_b32 s24, v254, 27
	v_readlane_b32 s25, v254, 28
	v_cndmask_b32_e32 v37, v37, v50, vcc
	v_rsq_f32_e32 v52, v37
	v_mov_b64_e32 v[50:51], s[24:25]
	v_mad_i64_i32 v[50:51], s[24:25], v25, s82, v[50:51]
	v_mul_f32_e32 v53, 0x45800000, v52
	v_lshl_add_u64 v[50:51], s[20:21], 1, v[50:51]
	v_cndmask_b32_e32 v56, v52, v53, vcc
	v_lshl_add_u64 v[60:61], v[180:181], 1, v[50:51]
	v_cvt_pk_bf16_f32 v50, v80, v81
	v_cvt_pk_bf16_f32 v51, v84, v85
	v_cvt_pk_bf16_f32 v52, v86, v87
	v_cvt_pk_bf16_f32 v53, v54, v88
	v_add_u32_e32 v37, 0xa0, v186
	global_store_dwordx4 v[60:61], v[50:53], off
	s_nop 1
	v_cvt_pk_bf16_f32 v50, v78, v79
	v_cvt_pk_bf16_f32 v51, v82, v83
	v_cvt_pk_bf16_f32 v52, v90, v91
	v_cvt_pk_bf16_f32 v53, v59, v89
	global_store_dwordx4 v[60:61], v[50:53], off offset:64
	v_pk_fma_f32 v[62:63], v[30:31], v[56:57], v[46:47] op_sel_hi:[1,0,1]
	v_fma_f32 v31, v20, v56, v36
	v_mov_b32_e32 v20, v29
	v_pk_fma_f32 v[64:65], v[38:39], v[56:57], v[42:43] op_sel_hi:[1,0,1]
	v_pk_fma_f32 v[70:71], v[26:27], v[56:57], v[22:23] op_sel_hi:[1,0,1]
	v_pk_fma_f32 v[74:75], v[18:19], v[56:57], v[34:35] op_sel_hi:[1,0,1]
	v_fma_f32 v26, v28, v56, v24
	v_pk_fma_f32 v[68:69], v[40:41], v[56:57], v[44:45] op_sel_hi:[1,0,1]
	v_pk_fma_f32 v[66:67], v[32:33], v[56:57], v[48:49] op_sel_hi:[1,0,1]
	s_and_b64 vcc, exec, s[38:39]
	v_pk_fma_f32 v[72:73], v[20:21], v[56:57], v[188:189] op_sel_hi:[1,0,1]
	s_cbranch_vccnz .LBB0_814
	v_pk_mul_f32 v[18:19], v[64:65], v[64:65]
	v_pk_mul_f32 v[20:21], v[68:69], v[68:69]
	v_add_f32_e32 v18, v18, v19
	v_add_f32_e32 v18, v20, v18
	v_pk_mul_f32 v[28:29], v[70:71], v[70:71]
	v_add_f32_e32 v18, v21, v18
	v_add_f32_e32 v18, v28, v18
	v_add_f32_e32 v20, v29, v18
	v_fmac_f32_e32 v20, v26, v26
	v_fmac_f32_e32 v20, v72, v72
	v_pk_mul_f32 v[18:19], v[62:63], v[62:63]
	v_mov_b32_e32 v30, v73
	v_add_f32_e32 v18, v18, v20
	v_add_f32_e32 v20, v19, v18
	v_pk_mul_f32 v[18:19], v[66:67], v[66:67]
	v_readlane_b32 s24, v254, 23
	v_add_f32_e32 v18, v18, v20
	v_add_f32_e32 v20, v19, v18
	v_pk_mul_f32 v[18:19], v[74:75], v[74:75]
	v_mov_b32_e32 v39, v0
	v_add_f32_e32 v18, v18, v20
	v_add_f32_e32 v20, v19, v18
	v_pk_mul_f32 v[18:19], v[30:31], v[30:31]
	v_readlane_b32 s25, v254, 24
	v_add_f32_e32 v19, v19, v20
	v_and_b32_e32 v20, 64, v224
	v_add_f32_e32 v18, v18, v19
	v_xor_b32_e32 v19, 16, v224
	v_add_u32_e32 v20, 64, v20
	v_cmp_lt_i32_e32 vcc, v19, v20
	s_nop 1
	v_cndmask_b32_e32 v19, v224, v19, vcc
	v_lshlrev_b32_e32 v19, 2, v19
	ds_bpermute_b32 v19, v19, v18
	s_waitcnt lgkmcnt(0)
	v_add_f32_e32 v18, v18, v19
	v_xor_b32_e32 v19, 32, v224
	v_cmp_lt_i32_e32 vcc, v19, v20
	s_nop 1
	v_cndmask_b32_e32 v19, v224, v19, vcc
	v_lshlrev_b32_e32 v19, 2, v19
	ds_bpermute_b32 v19, v19, v18
	s_waitcnt lgkmcnt(0)
	v_add_f32_e32 v18, v18, v19
	v_fmamk_f32 v18, v18, 0x3c800000, v223
	v_cmp_gt_f32_e32 vcc, s95, v18
	v_mul_f32_e32 v19, 0x4b800000, v18
	s_nop 0
	v_cndmask_b32_e32 v18, v18, v19, vcc
	v_rsq_f32_e32 v18, v18
	s_nop 0
	v_mul_f32_e32 v19, 0x45800000, v18
	v_cndmask_b32_e32 v76, v18, v19, vcc
	ds_read_b128 v[18:21], v215 offset:16
	ds_read_b128 v[50:53], v215
	v_mul_f32_e32 v25, v26, v76
	ds_read_b128 v[26:29], v215 offset:144
	ds_read_b128 v[54:57], v215 offset:128
	v_pk_mul_f32 v[62:63], v[62:63], v[76:77] op_sel_hi:[1,0]
	v_pk_mul_f32 v[64:65], v[64:65], v[76:77] op_sel_hi:[1,0]
	s_waitcnt lgkmcnt(3)
	v_mul_f32_e32 v20, v20, v25
	v_mul_f32_e32 v25, v31, v76
	s_waitcnt lgkmcnt(1)
	v_mul_f32_e32 v78, v28, v25
	v_lshlrev_b32_e32 v25, 7, v37
	v_and_b32_e32 v38, 0xfff80, v25
	v_lshl_add_u64 v[30:31], s[24:25], 0, v[38:39]
	v_readlane_b32 s24, v254, 25
	v_readlane_b32 s25, v254, 26
	v_lshl_add_u64 v[40:41], v[30:31], 0, v[182:183]
	v_lshl_add_u64 v[38:39], s[24:25], 0, v[38:39]
	v_lshl_add_u64 v[80:81], v[38:39], 0, v[182:183]
	s_waitcnt lgkmcnt(0)
	v_pk_mul_f32 v[54:55], v[54:55], v[62:63]
	v_pk_mul_f32 v[50:51], v[50:51], v[64:65]
	v_mov_b32_e32 v28, v21
	s_waitcnt vmcnt(2)
	v_mov_b64_e32 v[58:59], v[236:237]
	v_mov_b64_e32 v[60:61], v[238:239]
	v_mov_b64_e32 v[30:31], v[240:241]
	v_mov_b64_e32 v[32:33], v[242:243]
	v_mov_b64_e32 v[80:81], v[244:245]
	v_mov_b64_e32 v[82:83], v[246:247]
	v_mov_b64_e32 v[38:39], v[248:249]
	v_mov_b64_e32 v[40:41], v[250:251]
	v_pk_mul_f32 v[62:63], v[80:81], v[54:55]
	v_pk_mul_f32 v[54:55], v[58:59], v[54:55]
	v_pk_fma_f32 v[64:65], v[58:59], v[50:51], v[62:63] neg_lo:[0,0,1] neg_hi:[0,0,1]
	v_pk_fma_f32 v[62:63], v[80:81], v[50:51], v[54:55]
	v_pk_mul_f32 v[50:51], v[68:69], v[76:77] op_sel_hi:[1,0]
	s_nop 0
	v_pk_mul_f32 v[50:51], v[52:53], v[50:51]
	v_pk_mul_f32 v[52:53], v[66:67], v[76:77] op_sel_hi:[1,0]
	s_nop 0
	v_pk_mul_f32 v[52:53], v[56:57], v[52:53]
	s_nop 0
	v_pk_mul_f32 v[54:55], v[82:83], v[52:53]
	v_pk_mul_f32 v[52:53], v[60:61], v[52:53]
	v_pk_fma_f32 v[68:69], v[60:61], v[50:51], v[54:55] neg_lo:[0,0,1] neg_hi:[0,0,1]
	v_pk_fma_f32 v[66:67], v[82:83], v[50:51], v[52:53]
	v_pk_mul_f32 v[50:51], v[70:71], v[76:77] op_sel_hi:[1,0]
	s_nop 0
	v_pk_mul_f32 v[18:19], v[18:19], v[50:51]
	v_pk_mul_f32 v[50:51], v[74:75], v[76:77] op_sel_hi:[1,0]
	s_nop 0
	v_pk_mul_f32 v[26:27], v[26:27], v[50:51]
	s_nop 0
	v_pk_mul_f32 v[50:51], v[38:39], v[26:27]
	v_pk_mul_f32 v[26:27], v[30:31], v[26:27]
	v_pk_fma_f32 v[70:71], v[30:31], v[18:19], v[50:51] neg_lo:[0,0,1] neg_hi:[0,0,1]
	v_pk_fma_f32 v[74:75], v[38:39], v[18:19], v[26:27]
	v_pk_mul_f32 v[26:27], v[72:73], v[76:77] op_sel_hi:[1,0]
	v_mul_f32_e32 v30, v32, v78
	v_pk_mul_f32 v[28:29], v[28:29], v[26:27]
	v_mul_f32_e32 v18, v40, v20
	v_mov_b32_e32 v79, v29
	v_mov_b32_e32 v21, v28
	v_pk_mul_f32 v[26:27], v[40:41], v[78:79]
	s_nop 0
	v_pk_fma_f32 v[26:27], v[32:33], v[20:21], v[26:27] neg_lo:[0,0,1] neg_hi:[0,0,1]
	v_mov_b32_e32 v32, v41
	v_pk_mul_f32 v[20:21], v[32:33], v[28:29]
	v_mov_b32_e32 v72, v27
	v_mov_b32_e32 v19, v20
	v_mov_b32_e32 v31, v21
	v_pk_add_f32 v[18:19], v[18:19], v[30:31]
	s_nop 0
	v_mov_b32_e32 v31, v18
	v_mov_b32_e32 v73, v19
	v_add_u32_e32 v222, 0xb0, v186
	v_lshlrev_b32_e32 v222, 7, v222
	v_and_b32_e32 v222, 0xfff80, v222
	v_mad_u64_u32 v[220:221], vcc, v222, 1, v[168:169]
	global_load_dwordx4 v[240:243], v[220:221], off offset:16
	global_load_dwordx4 v[236:239], v[220:221], off
	v_add_co_u32_e32 v220, vcc, 0x100000, v220
	s_nop 1
	v_addc_co_u32_e32 v221, vcc, 0, v221, vcc
	global_load_dwordx4 v[248:251], v[220:221], off offset:16
	global_load_dwordx4 v[244:247], v[220:221], off
.LBB0_814:
	v_fmamk_f32 v18, v187, 0x3a800000, v223
	v_mul_f32_e32 v19, 0x4b800000, v18
	v_cmp_gt_f32_e32 vcc, s95, v18
	v_readlane_b32 s24, v254, 27
	v_readlane_b32 s25, v254, 28
	v_cndmask_b32_e32 v18, v18, v19, vcc
	v_rsq_f32_e32 v20, v18
	v_mov_b64_e32 v[18:19], s[24:25]
	v_mad_i64_i32 v[18:19], s[24:25], v37, s82, v[18:19]
	v_mul_f32_e32 v21, 0x45800000, v20
	v_lshl_add_u64 v[18:19], s[20:21], 1, v[18:19]
	v_cndmask_b32_e32 v28, v20, v21, vcc
	v_lshl_add_u64 v[32:33], v[180:181], 1, v[18:19]
	v_cvt_pk_bf16_f32 v18, v64, v65
	v_cvt_pk_bf16_f32 v19, v68, v69
	v_cvt_pk_bf16_f32 v20, v70, v71
	v_cvt_pk_bf16_f32 v21, v26, v72
	v_add_u32_e32 v50, 0xb0, v186
	global_store_dwordx4 v[32:33], v[18:21], off
	s_nop 1
	v_cvt_pk_bf16_f32 v18, v62, v63
	v_cvt_pk_bf16_f32 v19, v66, v67
	v_cvt_pk_bf16_f32 v20, v74, v75
	v_cvt_pk_bf16_f32 v21, v31, v73
	global_store_dwordx4 v[32:33], v[18:21], off offset:64
	v_fmac_f32_e32 v36, v4, v28
	v_mov_b32_e32 v4, v9
	v_pk_fma_f32 v[32:33], v[14:15], v[28:29], v[42:43] op_sel_hi:[1,0,1]
	v_pk_fma_f32 v[30:31], v[10:11], v[28:29], v[46:47] op_sel_hi:[1,0,1]
	v_pk_fma_f32 v[46:47], v[6:7], v[28:29], v[22:23] op_sel_hi:[1,0,1]
	v_pk_fma_f32 v[42:43], v[2:3], v[28:29], v[34:35] op_sel_hi:[1,0,1]
	v_fmac_f32_e32 v24, v8, v28
	v_pk_fma_f32 v[38:39], v[16:17], v[28:29], v[44:45] op_sel_hi:[1,0,1]
	v_pk_fma_f32 v[34:35], v[12:13], v[28:29], v[48:49] op_sel_hi:[1,0,1]
	s_and_b64 vcc, exec, s[38:39]
	v_pk_fma_f32 v[40:41], v[4:5], v[28:29], v[188:189] op_sel_hi:[1,0,1]
	s_cbranch_vccnz .LBB0_794
	v_pk_mul_f32 v[2:3], v[32:33], v[32:33]
	v_pk_mul_f32 v[4:5], v[38:39], v[38:39]
	v_add_f32_e32 v2, v2, v3
	v_add_f32_e32 v2, v4, v2
	v_pk_mul_f32 v[6:7], v[46:47], v[46:47]
	v_add_f32_e32 v2, v5, v2
	v_add_f32_e32 v2, v6, v2
	v_add_f32_e32 v4, v7, v2
	v_fmac_f32_e32 v4, v24, v24
	v_fmac_f32_e32 v4, v40, v40
	v_pk_mul_f32 v[2:3], v[30:31], v[30:31]
	v_readlane_b32 s24, v254, 23
	v_add_f32_e32 v2, v2, v4
	v_add_f32_e32 v4, v3, v2
	v_pk_mul_f32 v[2:3], v[34:35], v[34:35]
	v_mov_b32_e32 v15, v0
	v_add_f32_e32 v2, v2, v4
	v_add_f32_e32 v4, v3, v2
	v_pk_mul_f32 v[2:3], v[42:43], v[42:43]
	v_readlane_b32 s25, v254, 24
	v_add_f32_e32 v2, v2, v4
	v_add_f32_e32 v4, v3, v2
	v_mov_b32_e32 v2, v41
	v_mov_b32_e32 v3, v36
	v_pk_mul_f32 v[2:3], v[2:3], v[2:3]
	s_nop 0
	v_add_f32_e32 v3, v3, v4
	v_and_b32_e32 v4, 64, v224
	v_add_f32_e32 v2, v2, v3
	v_xor_b32_e32 v3, 16, v224
	v_add_u32_e32 v4, 64, v4
	v_cmp_lt_i32_e32 vcc, v3, v4
	s_nop 1
	v_cndmask_b32_e32 v3, v224, v3, vcc
	v_lshlrev_b32_e32 v3, 2, v3
	ds_bpermute_b32 v3, v3, v2
	s_waitcnt lgkmcnt(0)
	v_add_f32_e32 v2, v2, v3
	v_xor_b32_e32 v3, 32, v224
	v_cmp_lt_i32_e32 vcc, v3, v4
	s_nop 1
	v_cndmask_b32_e32 v3, v224, v3, vcc
	v_lshlrev_b32_e32 v3, 2, v3
	ds_bpermute_b32 v3, v3, v2
	s_waitcnt lgkmcnt(0)
	v_add_f32_e32 v2, v2, v3
	v_fmamk_f32 v2, v2, 0x3c800000, v223
	v_cmp_gt_f32_e32 vcc, s95, v2
	v_mul_f32_e32 v3, 0x4b800000, v2
	s_nop 0
	v_cndmask_b32_e32 v2, v2, v3, vcc
	v_rsq_f32_e32 v2, v2
	s_nop 0
	v_mul_f32_e32 v3, 0x45800000, v2
	v_cndmask_b32_e32 v44, v2, v3, vcc
	ds_read_b128 v[2:5], v215 offset:16
	ds_read_b128 v[18:21], v215
	v_mul_f32_e32 v6, v24, v44
	v_mul_f32_e32 v10, v36, v44
	v_pk_mul_f32 v[30:31], v[30:31], v[44:45] op_sel_hi:[1,0]
	v_pk_mul_f32 v[32:33], v[32:33], v[44:45] op_sel_hi:[1,0]
	s_waitcnt lgkmcnt(1)
	v_mul_f32_e32 v4, v4, v6
	ds_read_b128 v[6:9], v215 offset:144
	ds_read_b128 v[22:25], v215 offset:128
	s_waitcnt lgkmcnt(2)
	v_pk_mul_f32 v[18:19], v[18:19], v[32:33]
	s_waitcnt lgkmcnt(1)
	v_mul_f32_e32 v36, v8, v10
	v_lshlrev_b32_e32 v8, 7, v50
	v_and_b32_e32 v14, 0xfff80, v8
	v_lshl_add_u64 v[10:11], s[24:25], 0, v[14:15]
	v_readlane_b32 s24, v254, 25
	v_readlane_b32 s25, v254, 26
	v_lshl_add_u64 v[16:17], v[10:11], 0, v[182:183]
	v_lshl_add_u64 v[14:15], s[24:25], 0, v[14:15]
	v_lshl_add_u64 v[48:49], v[14:15], 0, v[182:183]
	s_waitcnt lgkmcnt(0)
	v_pk_mul_f32 v[22:23], v[22:23], v[30:31]
	v_mov_b32_e32 v8, v5
	s_waitcnt vmcnt(2)
	v_mov_b64_e32 v[26:27], v[236:237]
	v_mov_b64_e32 v[28:29], v[238:239]
	v_mov_b64_e32 v[10:11], v[240:241]
	v_mov_b64_e32 v[12:13], v[242:243]
	v_mov_b64_e32 v[52:53], v[244:245]
	v_mov_b64_e32 v[54:55], v[246:247]
	v_mov_b64_e32 v[14:15], v[248:249]
	v_mov_b64_e32 v[16:17], v[250:251]
	v_pk_mul_f32 v[30:31], v[52:53], v[22:23]
	v_pk_mul_f32 v[22:23], v[26:27], v[22:23]
	v_pk_fma_f32 v[32:33], v[26:27], v[18:19], v[30:31] neg_lo:[0,0,1] neg_hi:[0,0,1]
	v_pk_fma_f32 v[30:31], v[52:53], v[18:19], v[22:23]
	v_pk_mul_f32 v[18:19], v[38:39], v[44:45] op_sel_hi:[1,0]
	s_nop 0
	v_pk_mul_f32 v[18:19], v[20:21], v[18:19]
	v_pk_mul_f32 v[20:21], v[34:35], v[44:45] op_sel_hi:[1,0]
	s_nop 0
	v_pk_mul_f32 v[20:21], v[24:25], v[20:21]
	s_nop 0
	v_pk_mul_f32 v[22:23], v[54:55], v[20:21]
	v_pk_mul_f32 v[20:21], v[28:29], v[20:21]
	v_pk_fma_f32 v[38:39], v[28:29], v[18:19], v[22:23] neg_lo:[0,0,1] neg_hi:[0,0,1]
	v_pk_fma_f32 v[34:35], v[54:55], v[18:19], v[20:21]
	v_pk_mul_f32 v[18:19], v[46:47], v[44:45] op_sel_hi:[1,0]
	s_nop 0
	v_pk_mul_f32 v[2:3], v[2:3], v[18:19]
	v_pk_mul_f32 v[18:19], v[42:43], v[44:45] op_sel_hi:[1,0]
	s_nop 0
	v_pk_mul_f32 v[6:7], v[6:7], v[18:19]
	s_nop 0
	v_pk_mul_f32 v[18:19], v[14:15], v[6:7]
	v_pk_mul_f32 v[6:7], v[10:11], v[6:7]
	v_pk_fma_f32 v[46:47], v[10:11], v[2:3], v[18:19] neg_lo:[0,0,1] neg_hi:[0,0,1]
	v_pk_mul_f32 v[10:11], v[40:41], v[44:45] op_sel_hi:[1,0]
	v_pk_fma_f32 v[42:43], v[14:15], v[2:3], v[6:7]
	v_pk_mul_f32 v[8:9], v[8:9], v[10:11]
	v_mul_f32_e32 v6, v12, v36
	v_mov_b32_e32 v37, v9
	v_mov_b32_e32 v5, v8
	v_pk_mul_f32 v[10:11], v[16:17], v[36:37]
	v_mul_f32_e32 v2, v16, v4
	v_pk_fma_f32 v[24:25], v[12:13], v[4:5], v[10:11] neg_lo:[0,0,1] neg_hi:[0,0,1]
	v_mov_b32_e32 v12, v17
	v_pk_mul_f32 v[4:5], v[12:13], v[8:9]
	v_mov_b32_e32 v40, v25
	v_mov_b32_e32 v3, v4
	v_mov_b32_e32 v7, v5
	v_pk_add_f32 v[36:37], v[2:3], v[6:7]
	s_nop 0
	v_mov_b32_e32 v41, v37
	s_branch .LBB0_794
